# SSM inter-chunk scan: initial-state (x0) load issued with the task's other loads instead of after the exchange barrier
# baseline (speedup 1.0000x reference)
; #define LAS __attribute__((address_space(3)))
; __global__ void __launch_bounds__(NWAVES * 64, 2) hybrid_fwd(Args args) {
;     ...
;             for (int w = vcu; w < 256; w += G) { const int b = w >> 7, g = (w >> 1) & 63, n = (w & 1) * 32 + (tid & 31), seg = tid >> 5;
;                 __syncthreads();
;                 const f32x2 A16 = P.apow_()[((size_t)g * 17 + 16) * 64 + n];
;                 f32x2 A256 = A16;
; #pragma unroll
;                 for (int z = 0; z < 4; ++z) A256 = (f32x2){A256.x * A256.x - A256.y * A256.y, 2.f * A256.x * A256.y};
;                 const float* sl = P.sloc_() + ((size_t)(g * 512 + b * 256 + seg * 16)) * 128 + n;
;                 float sre[16], sim[16];
; #pragma unroll
;                 for (int j = 0; j < 16; ++j) { sre[j] = sl[j * 128]; sim[j] = sl[j * 128 + 64]; }
;                 float tr = 0.f, ti = 0.f;
; #pragma unroll
;                 for (int j = 0; j < 16; ++j) { const float nr = A16.x * tr - A16.y * ti + sre[j], ni = A16.x * ti + A16.y * tr + sim[j]; tr = nr; ti = ni; }
;                 LAS f32x2* T = (LAS f32x2*)lds;
;                 T[seg * 32 + (tid & 31)] = (f32x2){tr, ti};
;                 __syncthreads();
.LBB0_598:
	s_bfe_u32 s20, s35, 0x60001
	s_lshl_b32 s21, s35, 5
	v_and_or_b32 v47, s21, 32, v174
	s_mul_i32 s21, s20, 0x440
	s_addk_i32 s21, 0x400
	v_or_b32_e32 v2, s21, v47
	v_lshlrev_b32_e32 v2, 3, v2
	s_waitcnt vmcnt(0)
	s_barrier
	global_load_dwordx2 v[4:5], v2, s[10:11]
	s_lshl_b32 s21, s35, 1
	s_lshl_b32 s20, s20, 9
	v_lshl_or_b32 v70, v47, 3, s20
	global_load_dwordx2 v[72:73], v70, s[16:17]
	s_and_b32 s21, s21, 0xffffff00
	s_add_i32 s21, s20, s21
	v_or_b32_e32 v20, s21, v29
	v_ashrrev_i32_e32 v21, 31, v20
	v_lshlrev_b64 v[6:7], 9, v[20:21]
	v_lshl_add_u64 v[6:7], s[14:15], 0, v[6:7]
	v_lshlrev_b32_e32 v2, 2, v47
	v_lshl_add_u64 v[6:7], v[6:7], 0, v[2:3]
	global_load_dword v49, v[6:7], off
	global_load_dword v48, v[6:7], off offset:256
	global_load_dword v18, v[6:7], off offset:512
	global_load_dword v19, v[6:7], off offset:768
	global_load_dword v46, v[6:7], off offset:1024
	global_load_dword v45, v[6:7], off offset:1280
	global_load_dword v16, v[6:7], off offset:1536
	global_load_dword v17, v[6:7], off offset:1792
	global_load_dword v44, v[6:7], off offset:2048
	global_load_dword v43, v[6:7], off offset:2304
	global_load_dword v14, v[6:7], off offset:2560
	global_load_dword v15, v[6:7], off offset:2816
	global_load_dword v42, v[6:7], off offset:3072
	global_load_dword v41, v[6:7], off offset:3328
	global_load_dword v12, v[6:7], off offset:3584
	global_load_dword v13, v[6:7], off offset:3840
	v_add_co_u32_e32 v22, vcc, s3, v6
	s_nop 1
	v_addc_co_u32_e32 v23, vcc, 0, v7, vcc
	global_load_dword v40, v[22:23], off
	global_load_dword v39, v[22:23], off offset:256
	global_load_dword v10, v[22:23], off offset:512
	global_load_dword v11, v[22:23], off offset:768
	global_load_dword v38, v[22:23], off offset:1024
	global_load_dword v37, v[22:23], off offset:1280
	global_load_dword v8, v[22:23], off offset:1536
	global_load_dword v9, v[22:23], off offset:1792
	global_load_dword v36, v[22:23], off offset:2048
	global_load_dword v35, v[22:23], off offset:2304
	global_load_dword v6, v[22:23], off offset:2560
	global_load_dword v7, v[22:23], off offset:2816
	global_load_dword v34, v[22:23], off offset:3072
	global_load_dword v21, v[22:23], off offset:3328
	global_load_dword v24, v[22:23], off offset:3584
	global_load_dword v25, v[22:23], off offset:3840
	s_waitcnt vmcnt(32)
	v_pk_mul_f32 v[22:23], v[4:5], 0 op_sel_hi:[1,0]
	s_nop 0
	v_sub_f32_e32 v2, v22, v23
	v_add_f32_e32 v22, v23, v22
	s_waitcnt vmcnt(30)
	v_add_f32_e32 v22, v22, v48
	v_add_f32_e32 v2, v2, v49
	v_pk_mul_f32 v[22:23], v[4:5], v[22:23] op_sel:[1,0] op_sel_hi:[0,0]
	v_pk_fma_f32 v[26:27], v[4:5], v[2:3], v[22:23] neg_lo:[0,0,1] neg_hi:[0,0,1]
	v_pk_fma_f32 v[22:23], v[4:5], v[2:3], v[22:23] op_sel_hi:[1,0,1]
	s_nop 0
	v_mov_b32_e32 v27, v23
	s_waitcnt vmcnt(28)
	v_pk_add_f32 v[22:23], v[26:27], v[18:19]
	s_nop 0
	v_pk_mul_f32 v[26:27], v[4:5], v[22:23]
	v_pk_mul_f32 v[22:23], v[4:5], v[22:23] op_sel:[1,0] op_sel_hi:[0,1]
	v_add_f32_e32 v22, v22, v23
	v_sub_f32_e32 v2, v26, v27
	s_waitcnt vmcnt(26)
	v_add_f32_e32 v22, v22, v45
	v_add_f32_e32 v2, v2, v46
	v_pk_mul_f32 v[22:23], v[4:5], v[22:23] op_sel:[1,0] op_sel_hi:[0,0]
	v_pk_fma_f32 v[26:27], v[4:5], v[2:3], v[22:23] neg_lo:[0,0,1] neg_hi:[0,0,1]
	v_pk_fma_f32 v[22:23], v[4:5], v[2:3], v[22:23] op_sel_hi:[1,0,1]
	s_nop 0
	v_mov_b32_e32 v27, v23
	s_waitcnt vmcnt(24)
	v_pk_add_f32 v[22:23], v[26:27], v[16:17]
	s_nop 0
	v_pk_mul_f32 v[26:27], v[4:5], v[22:23]
	v_pk_mul_f32 v[22:23], v[4:5], v[22:23] op_sel:[1,0] op_sel_hi:[0,1]
	v_add_f32_e32 v22, v22, v23
	v_sub_f32_e32 v2, v26, v27
	s_waitcnt vmcnt(22)
	v_add_f32_e32 v22, v22, v43
	v_add_f32_e32 v2, v2, v44
	v_pk_mul_f32 v[22:23], v[4:5], v[22:23] op_sel:[1,0] op_sel_hi:[0,0]
	v_pk_fma_f32 v[26:27], v[4:5], v[2:3], v[22:23] neg_lo:[0,0,1] neg_hi:[0,0,1]
	v_pk_fma_f32 v[22:23], v[4:5], v[2:3], v[22:23] op_sel_hi:[1,0,1]
	s_nop 0
	v_mov_b32_e32 v27, v23
	s_waitcnt vmcnt(20)
	v_pk_add_f32 v[22:23], v[26:27], v[14:15]
	s_nop 0
	v_pk_mul_f32 v[26:27], v[4:5], v[22:23]
	v_pk_mul_f32 v[22:23], v[4:5], v[22:23] op_sel:[1,0] op_sel_hi:[0,1]
	v_add_f32_e32 v22, v22, v23
	v_sub_f32_e32 v2, v26, v27
	s_waitcnt vmcnt(18)
	v_add_f32_e32 v22, v22, v41
	v_add_f32_e32 v2, v2, v42
	v_pk_mul_f32 v[22:23], v[4:5], v[22:23] op_sel:[1,0] op_sel_hi:[0,0]
	v_pk_fma_f32 v[26:27], v[4:5], v[2:3], v[22:23] neg_lo:[0,0,1] neg_hi:[0,0,1]
	v_pk_fma_f32 v[22:23], v[4:5], v[2:3], v[22:23] op_sel_hi:[1,0,1]
	s_nop 0
	v_mov_b32_e32 v27, v23
	s_waitcnt vmcnt(16)
	v_pk_add_f32 v[22:23], v[26:27], v[12:13]
	s_nop 0
	v_pk_mul_f32 v[26:27], v[4:5], v[22:23]
	v_pk_mul_f32 v[22:23], v[4:5], v[22:23] op_sel:[1,0] op_sel_hi:[0,1]
	v_add_f32_e32 v22, v22, v23
	v_sub_f32_e32 v2, v26, v27
	s_waitcnt vmcnt(14)
	v_add_f32_e32 v22, v22, v39
	v_add_f32_e32 v2, v2, v40
	v_pk_mul_f32 v[22:23], v[4:5], v[22:23] op_sel:[1,0] op_sel_hi:[0,0]
	v_pk_fma_f32 v[26:27], v[4:5], v[2:3], v[22:23] neg_lo:[0,0,1] neg_hi:[0,0,1]
	v_pk_fma_f32 v[22:23], v[4:5], v[2:3], v[22:23] op_sel_hi:[1,0,1]
	s_nop 0
	v_mov_b32_e32 v27, v23
	s_waitcnt vmcnt(12)
	v_pk_add_f32 v[22:23], v[26:27], v[10:11]
	s_nop 0
	v_pk_mul_f32 v[26:27], v[4:5], v[22:23]
	v_pk_mul_f32 v[22:23], v[4:5], v[22:23] op_sel:[1,0] op_sel_hi:[0,1]
	v_add_f32_e32 v22, v22, v23
	v_sub_f32_e32 v2, v26, v27
	s_waitcnt vmcnt(10)
	v_add_f32_e32 v22, v22, v37
	v_add_f32_e32 v2, v2, v38
	v_pk_mul_f32 v[22:23], v[4:5], v[22:23] op_sel:[1,0] op_sel_hi:[0,0]
	v_pk_fma_f32 v[26:27], v[4:5], v[2:3], v[22:23] neg_lo:[0,0,1] neg_hi:[0,0,1]
	v_pk_fma_f32 v[22:23], v[4:5], v[2:3], v[22:23] op_sel_hi:[1,0,1]
	s_nop 0
	v_mov_b32_e32 v27, v23
	s_waitcnt vmcnt(8)
	v_pk_add_f32 v[22:23], v[26:27], v[8:9]
	s_nop 0
	v_pk_mul_f32 v[26:27], v[4:5], v[22:23]
	v_pk_mul_f32 v[22:23], v[4:5], v[22:23] op_sel:[1,0] op_sel_hi:[0,1]
	v_add_f32_e32 v22, v22, v23
	v_sub_f32_e32 v2, v26, v27
	s_waitcnt vmcnt(6)
	v_add_f32_e32 v22, v22, v35
	v_add_f32_e32 v2, v2, v36
	v_pk_mul_f32 v[22:23], v[4:5], v[22:23] op_sel:[1,0] op_sel_hi:[0,0]
	v_pk_fma_f32 v[26:27], v[4:5], v[2:3], v[22:23] neg_lo:[0,0,1] neg_hi:[0,0,1]
	v_pk_fma_f32 v[22:23], v[4:5], v[2:3], v[22:23] op_sel_hi:[1,0,1]
	s_nop 0
	v_mov_b32_e32 v27, v23
	s_waitcnt vmcnt(4)
	v_pk_add_f32 v[22:23], v[26:27], v[6:7]
	s_nop 0
	v_pk_mul_f32 v[26:27], v[4:5], v[22:23]
	v_pk_mul_f32 v[22:23], v[4:5], v[22:23] op_sel:[1,0] op_sel_hi:[0,1]
	v_add_f32_e32 v22, v22, v23
	v_sub_f32_e32 v2, v26, v27
	s_waitcnt vmcnt(2)
	v_add_f32_e32 v22, v22, v21
	v_add_f32_e32 v2, v2, v34
	v_pk_mul_f32 v[22:23], v[4:5], v[22:23] op_sel:[1,0] op_sel_hi:[0,0]
	v_pk_fma_f32 v[26:27], v[4:5], v[2:3], v[22:23] neg_lo:[0,0,1] neg_hi:[0,0,1]
	v_pk_fma_f32 v[22:23], v[4:5], v[2:3], v[22:23] op_sel_hi:[1,0,1]
	v_lshl_or_b32 v2, v47, 3, s20
	v_mov_b32_e32 v27, v23
	s_waitcnt vmcnt(0)
	v_pk_add_f32 v[22:23], v[26:27], v[24:25]
	ds_write_b64 v30, v[22:23]
	s_waitcnt lgkmcnt(0)
	s_barrier
; #define LAS __attribute__((address_space(3)))
; __global__ void __launch_bounds__(NWAVES * 64, 2) hybrid_fwd(Args args) {
;     ...
;                 f32x2 A256 = A16;
; #pragma unroll
;                 for (int z = 0; z < 4; ++z) A256 = (f32x2){A256.x * A256.x - A256.y * A256.y, 2.f * A256.x * A256.y};
;                 const float* sl = P.sloc_() + ((size_t)(g * 512 + b * 256 + seg * 16)) * 128 + n;
;                 float sre[16], sim[16];
; #pragma unroll
;                 for (int j = 0; j < 16; ++j) { sre[j] = sl[j * 128]; sim[j] = sl[j * 128 + 64]; }
;                 float tr = 0.f, ti = 0.f;
; #pragma unroll
;                 for (int j = 0; j < 16; ++j) { const float nr = A16.x * tr - A16.y * ti + sre[j], ni = A16.x * ti + A16.y * tr + sim[j]; tr = nr; ti = ni; }
;                 LAS f32x2* T = (LAS f32x2*)lds;
;                 T[seg * 32 + (tid & 31)] = (f32x2){tr, ti};
;                 __syncthreads();
;                 const f32x2 x0v = P.x0_()[g * 64 + n]; float xr = x0v.x, xi = x0v.y;
;                 for (int s2 = 0; s2 < seg; ++s2) { const f32x2 tv = T[s2 * 32 + (tid & 31)]; const float nr = A256.x * xr - A256.y * xi + tv.x, ni = A256.x * xi + A256.y * xr + tv.y; xr = nr; xi = ni; }
	v_mov_b64_e32 v[22:23], v[72:73]
	s_and_saveexec_b64 s[20:21], s[0:1]
	s_cbranch_execz .LBB0_597
	v_pk_mul_f32 v[24:25], v[4:5], v[4:5]
	s_nop 0
	v_sub_f32_e32 v2, v24, v25
	v_add_f32_e32 v24, v4, v4
	v_mul_f32_e32 v24, v5, v24
	v_mul_f32_e32 v25, v2, v2
	v_add_f32_e32 v2, v2, v2
	v_mul_f32_e32 v2, v24, v2
	v_fma_f32 v25, -v24, v24, v25
	v_mul_f32_e32 v24, v2, v2
	v_fma_f32 v24, v25, v25, -v24
	v_add_f32_e32 v25, v25, v25
	v_mul_f32_e32 v2, v2, v25
	v_mul_f32_e32 v25, v2, v2
	v_add_f32_e32 v26, v24, v24
	v_fma_f32 v24, v24, v24, -v25
	v_mul_f32_e32 v26, v2, v26
	v_mov_b32_e32 v2, 0
	s_and_saveexec_b64 s[22:23], s[6:7]
	s_cbranch_execz .LBB0_603
	v_mov_b32_e32 v25, v24
	v_mov_b32_e32 v27, v26
	s_mov_b32 s36, 0
	s_mov_b64 s[28:29], 0
	v_mov_b32_e32 v2, v31
